# attention skip threshold computed once per workgroup at kernel start and parked in an unused LDS control word, read back at the attention head
# baseline (speedup 1.0000x reference)
.Lssa_exit:
	v_readfirstlane_b32 s79, v208
	v_cmp_gt_u32_e64 s[4:5], 32, v208
	s_load_dwordx2 s[6:7], s[0:1], 0x28
	s_load_dwordx2 s[8:9], s[0:1], 0x30
	v_lshlrev_b32_e32 v0, 2, v210
	s_waitcnt lgkmcnt(0)
	global_load_dword v1, v0, s[6:7]
	global_load_dword v2, v0, s[8:9]
	v_mbcnt_lo_u32_b32 v0, -1, 0
	v_mbcnt_hi_u32_b32 v0, -1, v0
	v_and_b32_e32 v3, 64, v0
	v_xor_b32_e32 v4, 1, v0
	v_add_u32_e32 v3, 64, v3
	v_cmp_lt_i32_e32 vcc, v4, v3
	v_xor_b32_e32 v5, 2, v0
	v_xor_b32_e32 v6, 4, v0
	v_cndmask_b32_e32 v4, v0, v4, vcc
	v_lshlrev_b32_e32 v4, 2, v4
	v_cmp_lt_i32_e32 vcc, v5, v3
	v_xor_b32_e32 v7, 8, v0
	v_xor_b32_e32 v8, 16, v0
	v_cndmask_b32_e32 v5, v0, v5, vcc
	v_lshlrev_b32_e32 v5, 2, v5
	v_cmp_lt_i32_e32 vcc, v6, v3
	v_xor_b32_e32 v9, 32, v0
	v_cndmask_b32_e32 v6, v0, v6, vcc
	v_lshlrev_b32_e32 v6, 2, v6
	v_cmp_lt_i32_e32 vcc, v7, v3
	s_waitcnt lgkmcnt(0)
	v_cndmask_b32_e32 v7, v0, v7, vcc
	v_lshlrev_b32_e32 v7, 2, v7
	v_cmp_lt_i32_e32 vcc, v8, v3
	s_waitcnt vmcnt(1)
	v_and_b32_e32 v10, 0x7fffffff, v1
	ds_bpermute_b32 v10, v4, v10
	s_waitcnt vmcnt(0)
	v_and_b32_e32 v11, 0x7fffffff, v2
	ds_bpermute_b32 v4, v4, v11
	v_max_f32_e64 v1, |v1|, |v1|
	v_max_f32_e64 v2, |v2|, |v2|
	s_waitcnt lgkmcnt(1)
	v_max_f32_e32 v10, v10, v10
	v_max_f32_e32 v1, v1, v10
	s_waitcnt lgkmcnt(0)
	v_max_f32_e32 v4, v4, v4
	v_max_f32_e32 v2, v2, v4
	ds_bpermute_b32 v4, v5, v1
	ds_bpermute_b32 v5, v5, v2
	s_waitcnt lgkmcnt(1)
	v_max_f32_e32 v4, v4, v4
	v_max_f32_e32 v1, v1, v4
	s_waitcnt lgkmcnt(0)
	v_max_f32_e32 v4, v5, v5
	v_max_f32_e32 v2, v2, v4
	ds_bpermute_b32 v4, v6, v1
	ds_bpermute_b32 v5, v6, v2
	v_cndmask_b32_e32 v6, v0, v8, vcc
	v_cmp_lt_i32_e32 vcc, v9, v3
	v_lshlrev_b32_e32 v3, 2, v6
	s_waitcnt lgkmcnt(1)
	v_max_f32_e32 v4, v4, v4
	v_max_f32_e32 v1, v1, v4
	s_waitcnt lgkmcnt(0)
	v_max_f32_e32 v4, v5, v5
	v_max_f32_e32 v2, v2, v4
	ds_bpermute_b32 v4, v7, v1
	ds_bpermute_b32 v5, v7, v2
	v_cndmask_b32_e32 v0, v0, v9, vcc
	s_waitcnt lgkmcnt(1)
	v_max_f32_e32 v4, v4, v4
	v_max_f32_e32 v1, v1, v4
	s_waitcnt lgkmcnt(0)
	v_max_f32_e32 v4, v5, v5
	ds_bpermute_b32 v5, v3, v1
	v_max_f32_e32 v2, v2, v4
	ds_bpermute_b32 v3, v3, v2
	v_lshlrev_b32_e32 v4, 2, v0
	s_waitcnt lgkmcnt(1)
	v_max_f32_e32 v0, v5, v5
	v_max_f32_e32 v1, v1, v0
	s_waitcnt lgkmcnt(0)
	v_max_f32_e32 v0, v3, v3
	v_max_f32_e32 v0, v2, v0
	ds_bpermute_b32 v3, v4, v1
	ds_bpermute_b32 v2, v4, v0
	s_waitcnt lgkmcnt(0)
	v_max_f32_e32 v3, v3, v3
	v_max_f32_e32 v1, v1, v1
	v_max_f32_e32 v1, v1, v3
	v_max_f32_e32 v2, v2, v2
	v_max_f32_e32 v0, v0, v0
	v_max_f32_e32 v0, v0, v2
	v_mul_f32_e32 v1, 0x3f866666, v1
	v_mul_f32_e32 v0, v0, v1
	v_mul_f32_e32 v0, 0x42800000, v0
	v_mul_f32_e32 v0, 0x3e38aa3b, v0
	v_fmaak_f32 v5, 2.0, v0, 0x42200000
	s_and_saveexec_b64 s[6:7], s[26:27]
	v_mov_b32_e32 v6, 0x22060
	ds_write_b32 v6, v5
	s_or_b64 exec, exec, s[6:7]
	s_waitcnt lgkmcnt(0)
	s_and_saveexec_b64 s[6:7], s[26:27]
	s_cbranch_execz .LBB0_24
	s_load_dwordx2 s[8:9], s[0:1], 0x110
	v_mov_b32_e32 v0, 0
	v_mov_b32_e32 v1, s99
	s_waitcnt lgkmcnt(0)
	global_load_dword v2, v0, s[8:9] offset:32 sc1
	s_waitcnt vmcnt(0)
	v_and_b32_e32 v2, 0xffff0000, v2
	v_cmp_eq_u32_e32 vcc, v2, v1
	s_and_b64 exec, exec, vcc
	s_cbranch_execz .LBB0_23
	s_mov_b64 s[10:11], 0

.LBB0_280:
	s_cmp_lt_i32 s3, 3
	s_cselect_b64 s[8:9], -1, 0
	s_and_b64 s[20:21], s[8:9], s[6:7]
	s_andn2_b64 vcc, exec, s[20:21]
	s_cbranch_vccnz .LBB0_517
	s_mov_b64 s[6:7], s[0:1]
	s_mov_b64 s[8:9], s[0:1]
	s_load_dwordx2 s[6:7], s[6:7], 0xa8
	s_mov_b64 s[10:11], s[0:1]
	s_load_dwordx2 s[8:9], s[8:9], 0xa8
	s_load_dwordx2 s[12:13], s[10:11], 0xa8
	s_mov_b64 s[10:11], s[0:1]
	s_load_dwordx2 s[14:15], s[10:11], 0xa8
	s_mov_b64 s[10:11], s[0:1]
	s_load_dwordx2 s[16:17], s[10:11], 0xa8
	s_mov_b64 s[10:11], s[0:1]
	s_load_dwordx2 s[18:19], s[10:11], 0x28
	s_mov_b64 s[10:11], s[0:1]
	s_load_dwordx2 s[22:23], s[10:11], 0x30
	s_mov_b64 s[10:11], s[0:1]
	s_waitcnt vmcnt(0)
	v_lshlrev_b32_e32 v0, 2, v210
	s_waitcnt lgkmcnt(0)
	v_mbcnt_lo_u32_b32 v0, -1, 0
	v_mbcnt_hi_u32_b32 v0, -1, v0
	v_and_b32_e32 v3, 64, v0
	v_xor_b32_e32 v4, 1, v0
	v_add_u32_e32 v3, 64, v3
	v_cmp_lt_i32_e32 vcc, v4, v3
	v_xor_b32_e32 v5, 2, v0
	v_xor_b32_e32 v6, 4, v0
	v_cndmask_b32_e32 v4, v0, v4, vcc
	v_lshlrev_b32_e32 v4, 2, v4
	v_cmp_lt_i32_e32 vcc, v5, v3
	v_xor_b32_e32 v7, 8, v0
	v_xor_b32_e32 v8, 16, v0
	v_cndmask_b32_e32 v5, v0, v5, vcc
	v_lshlrev_b32_e32 v5, 2, v5
	v_cmp_lt_i32_e32 vcc, v6, v3
	v_xor_b32_e32 v9, 32, v0
	s_load_dwordx2 s[10:11], s[10:11], 0xa8
	v_cndmask_b32_e32 v6, v0, v6, vcc
	v_lshlrev_b32_e32 v6, 2, v6
	v_cmp_lt_i32_e32 vcc, v7, v3
	s_waitcnt lgkmcnt(0)
	s_add_u32 s38, s10, 0x44000
	v_cndmask_b32_e32 v7, v0, v7, vcc
	v_lshlrev_b32_e32 v7, 2, v7
	v_cmp_lt_i32_e32 vcc, v8, v3
	s_addc_u32 s39, s11, 0
	v_and_b32_e32 v10, 0x7fffffff, v1
	v_and_b32_e32 v11, 0x7fffffff, v2
	v_max_f32_e64 v1, |v1|, |v1|
	v_max_f32_e64 v2, |v2|, |v2|
	s_waitcnt lgkmcnt(1)
	v_max_f32_e32 v10, v10, v10
	v_max_f32_e32 v1, v1, v10
	s_waitcnt lgkmcnt(0)
	v_max_f32_e32 v4, v4, v4
	v_max_f32_e32 v2, v2, v4
	s_waitcnt lgkmcnt(1)
	v_max_f32_e32 v4, v4, v4
	v_max_f32_e32 v1, v1, v4
	s_waitcnt lgkmcnt(0)
	v_max_f32_e32 v4, v5, v5
	v_max_f32_e32 v2, v2, v4
	v_cndmask_b32_e32 v6, v0, v8, vcc
	v_cmp_lt_i32_e32 vcc, v9, v3
	v_lshlrev_b32_e32 v3, 2, v6
	s_waitcnt lgkmcnt(1)
	v_max_f32_e32 v4, v4, v4
	v_max_f32_e32 v1, v1, v4
	s_waitcnt lgkmcnt(0)
	v_max_f32_e32 v4, v5, v5
	v_max_f32_e32 v2, v2, v4
	v_cndmask_b32_e32 v0, v0, v9, vcc
	s_waitcnt lgkmcnt(1)
	v_max_f32_e32 v4, v4, v4
	v_max_f32_e32 v1, v1, v4
	s_waitcnt lgkmcnt(0)
	v_max_f32_e32 v4, v5, v5
	v_max_f32_e32 v2, v2, v4
	v_lshlrev_b32_e32 v4, 2, v0
	s_waitcnt lgkmcnt(1)
	v_max_f32_e32 v0, v5, v5
	v_max_f32_e32 v1, v1, v0
	s_waitcnt lgkmcnt(0)
	v_max_f32_e32 v0, v3, v3
	v_max_f32_e32 v0, v2, v0
	s_and_saveexec_b64 s[10:11], s[26:27]
	s_cbranch_execz .LBB0_315
	s_mov_b64 s[22:23], exec
	v_mbcnt_lo_u32_b32 v4, s22, 0
	v_mbcnt_hi_u32_b32 v4, s23, v4
	s_and_b32 s44, s60, 7
	v_cmp_eq_u32_e32 vcc, 0, v4
	s_and_saveexec_b64 s[18:19], vcc
	s_cbranch_execz .LBB0_284
	s_lshl_b32 s24, s44, 8
	s_bcnt1_i32_b64 s22, s[22:23]
	v_mov_b32_e32 v5, s24
	v_mov_b32_e32 v6, s22
	s_cmp_eq_u32 s101, 1
	s_cbranch_scc1 .Lattn_tk0_have
	global_atomic_add v5, v5, v6, s[38:39] sc0
	s_branch .Lattn_tk0_done

.LBB0_315:
	s_or_b64 exec, exec, s[10:11]
	s_add_i32 s68, 0, 0x22040
	v_mov_b32_e32 v4, s68
	s_waitcnt lgkmcnt(0)
	s_barrier
	ds_read_b32 v4, v4
	v_writelane_b32 v255, s96, 1
	v_writelane_b32 v255, s79, 3
	s_mov_b32 s11, 0
	s_waitcnt lgkmcnt(0)
	v_cmp_gt_i32_e32 vcc, 0, v4
	v_readfirstlane_b32 s88, v4
	s_cbranch_vccnz .LBB0_447
	s_add_u32 s69, s6, 0x6600000
	s_addc_u32 s70, s7, 0
	s_add_u32 s71, s8, 0x8600000
	s_addc_u32 s72, s9, 0
	s_add_u32 s73, s12, 0xa600000
	s_addc_u32 s74, s13, 0
	s_add_u32 s75, s14, 0xc600000
	s_addc_u32 s76, s15, 0
	s_add_u32 s77, s16, 0x200000
	s_addc_u32 s78, s17, 0
	s_and_b32 s79, s60, 7
	s_lshl_b32 s6, s79, 8
	s_add_u32 s12, s38, s6
	s_addc_u32 s13, s39, 0
	s_add_i32 s6, s60, 1
	s_and_b32 s80, s6, 7
	s_lshl_b32 s6, s80, 8
	s_add_u32 s14, s38, s6
	s_addc_u32 s15, s39, 0
	s_add_i32 s6, s60, 2
	s_and_b32 s81, s6, 7
	s_lshl_b32 s6, s81, 8
	s_add_u32 s16, s38, s6
	s_addc_u32 s17, s39, 0
	s_add_i32 s6, s60, 3
	s_and_b32 s82, s6, 7
	s_lshl_b32 s6, s82, 8
	s_add_u32 s18, s38, s6
	s_addc_u32 s19, s39, 0
	s_xor_b32 s83, s79, 4
	s_lshl_b32 s6, s83, 8
	s_add_u32 s22, s38, s6
	s_addc_u32 s23, s39, 0
	s_add_i32 s6, s60, 5
	s_and_b32 s84, s6, 7
	s_lshl_b32 s6, s84, 8
	s_add_u32 s24, s38, s6
	s_addc_u32 s25, s39, 0
	s_add_i32 s6, s60, 6
	s_and_b32 s85, s6, 7
	v_max_f32_e32 v3, v3, v3
	v_max_f32_e32 v1, v1, v1
	s_lshl_b32 s6, s85, 8
	v_max_f32_e32 v1, v1, v3
	v_max_f32_e32 v2, v2, v2
	v_max_f32_e32 v0, v0, v0
	s_add_u32 s36, s38, s6
	v_max_f32_e32 v0, v0, v2
	v_mul_f32_e32 v1, 0x3f866666, v1
	s_addc_u32 s37, s39, 0
	s_add_i32 s60, s60, -1
	v_mul_f32_e32 v0, v0, v1
	s_and_b32 s86, s60, 7
	v_mul_f32_e32 v0, 0x42800000, v0
	s_lshl_b32 s6, s86, 8
	v_mul_f32_e32 v0, 0x3e38aa3b, v0
	s_add_u32 s38, s38, s6
	s_mov_b32 s50, 0xfffe0000
	v_fmaak_f32 v201, 2.0, v0, 0x42200000
	v_mov_b32_e32 v202, 0x22060
	ds_read_b32 v201, v202
	s_waitcnt lgkmcnt(0)
	s_addc_u32 s39, s39, 0
	v_mov_b32_e32 v1, 0
	s_movk_i32 s87, 0x7f
	s_movk_i32 s90, 0x80
	s_mov_b64 s[40:41], 0x20000
	s_add_i32 s95, 0, 0x14800
	s_mov_b64 s[42:43], 0x2000
	s_mov_b64 s[44:45], 0x40000
	s_mov_b64 s[46:47], 0x60000
	s_add_i32 s96, 0, 0x14a00
	s_mov_b64 s[48:49], 0xa0000
	s_mov_b32 s51, -1
	s_mov_b32 s97, 0x42700000
	v_mov_b32_e32 v202, 0xff800000
	s_branch .LBB0_318
